# EpiRes (out-proj and FFN-down residual epilogues): non-temporal hint on the read-once residual loads
# baseline (speedup 1.0000x reference)
;     __device__ __forceinline__ void operator()(const f32x4 (&acc)[2][2][4][2], const Unit& u, int wr, int wc, int fr, int fq) const {
;         const int row0 = u.pm * BM + wr * 64 + fr, col0 = u.pn * BM + wc * 32 + 4 * fq;
; #pragma unroll
;         for (int ai = 0; ai < 2; ++ai)
; #pragma unroll
;             for (int m2 = 0; m2 < 2; ++m2) {
;                 f32x4 xv[2][2][2];
; #pragma unroll
;                 for (int mm = 0; mm < 2; ++mm) { const size_t off = (size_t)(row0 + ai * HALF + (2 * m2 + mm) * 16) * 1024 + col0;
; #pragma unroll
;                     for (int bj = 0; bj < 2; ++bj)
; #pragma unroll
;                         for (int n = 0; n < 2; ++n) xv[mm][bj][n] = *(const f32x4*)(xin + off + bj * HALF + n * 16); }
; #pragma unroll
;                 for (int mm = 0; mm < 2; ++mm) { const size_t off = (size_t)(row0 + ai * HALF + (2 * m2 + mm) * 16) * 1024 + col0;
; #pragma unroll
;                     for (int bj = 0; bj < 2; ++bj)
; #pragma unroll
;                         for (int n = 0; n < 2; ++n) *(f32x4*)(out + off + bj * HALF + n * 16) = xv[mm][bj][n] + acc[ai][bj][2 * m2 + mm][n]; }
;                 asm volatile("" ::: "memory");
.LBB0_1006:
	v_lshl_or_b32 v136, s68, 8, v146
	v_lshl_add_u32 v142, s69, 8, v144
	v_ashrrev_i32_e32 v137, 31, v136
	v_readlane_b32 s18, v254, 61
	v_lshlrev_b64 v[136:137], 2, v[136:137]
	v_readlane_b32 s19, v254, 62
	v_ashrrev_i32_e32 v143, 31, v142
	v_or_b32_e32 v164, 16, v142
	v_lshl_add_u64 v[138:139], s[18:19], 0, v[136:137]
	v_lshlrev_b64 v[140:141], 12, v[142:143]
	v_ashrrev_i32_e32 v165, 31, v164
	v_lshl_add_u64 v[160:161], v[138:139], 0, v[140:141]
	v_lshlrev_b64 v[180:181], 12, v[164:165]
	global_load_dwordx4 v[148:151], v[160:161], off nt
	global_load_dwordx4 v[152:155], v[160:161], off offset:64 nt
	global_load_dwordx4 v[156:159], v[160:161], off offset:512 nt
	s_nop 0
	global_load_dwordx4 v[160:163], v[160:161], off offset:576 nt
	v_lshl_add_u64 v[176:177], v[138:139], 0, v[180:181]
	global_load_dwordx4 v[164:167], v[176:177], off nt
	global_load_dwordx4 v[168:171], v[176:177], off offset:64 nt
	global_load_dwordx4 v[172:175], v[176:177], off offset:512 nt
	s_nop 0
	global_load_dwordx4 v[176:179], v[176:177], off offset:576 nt
	s_mov_b64 s[18:19], 0x80000
	s_andn2_b64 vcc, exec, s[4:5]
	s_waitcnt vmcnt(0)
	v_pk_add_f32 v[126:127], v[126:127], v[148:149]
	v_lshl_add_u64 v[148:149], s[6:7], 0, v[140:141]
	v_lshl_add_u64 v[148:149], v[148:149], 0, v[136:137]
	v_pk_add_f32 v[112:113], v[112:113], v[158:159]
	v_pk_add_f32 v[110:111], v[110:111], v[156:157]
	global_store_dwordx4 v[148:149], v[110:113], off offset:512
	v_pk_add_f32 v[108:109], v[108:109], v[162:163]
	v_pk_add_f32 v[106:107], v[106:107], v[160:161]
	v_lshl_add_u64 v[110:111], s[6:7], 0, v[180:181]
	v_lshl_add_u64 v[110:111], v[110:111], 0, v[136:137]
	v_pk_add_f32 v[100:101], v[100:101], v[178:179]
	v_pk_add_f32 v[98:99], v[98:99], v[176:177]
	global_store_dwordx4 v[148:149], v[106:109], off offset:576
	global_store_dwordx4 v[110:111], v[98:101], off offset:576
	v_pk_add_f32 v[128:129], v[128:129], v[150:151]
	v_pk_add_f32 v[108:109], v[120:121], v[166:167]
	v_pk_add_f32 v[106:107], v[118:119], v[164:165]
	v_or_b32_e32 v98, 32, v142
	v_pk_add_f32 v[124:125], v[124:125], v[154:155]
	v_pk_add_f32 v[122:123], v[122:123], v[152:153]
	global_store_dwordx4 v[110:111], v[106:109], off
	v_pk_add_f32 v[104:105], v[104:105], v[174:175]
	v_pk_add_f32 v[102:103], v[102:103], v[172:173]
	v_pk_add_f32 v[108:109], v[116:117], v[170:171]
	v_pk_add_f32 v[106:107], v[114:115], v[168:169]
	v_ashrrev_i32_e32 v99, 31, v98
	global_store_dwordx4 v[148:149], v[126:129], off
	global_store_dwordx4 v[148:149], v[122:125], off offset:64
	global_store_dwordx4 v[110:111], v[106:109], off offset:64
	global_store_dwordx4 v[110:111], v[102:105], off offset:512
	v_lshlrev_b64 v[148:149], 12, v[98:99]
	v_or_b32_e32 v114, 48, v142
	v_lshl_add_u64 v[110:111], v[138:139], 0, v[148:149]
	v_ashrrev_i32_e32 v115, 31, v114
	global_load_dwordx4 v[98:101], v[110:111], off nt
	global_load_dwordx4 v[102:105], v[110:111], off offset:64 nt
	global_load_dwordx4 v[106:109], v[110:111], off offset:512 nt
	s_nop 0
	global_load_dwordx4 v[110:113], v[110:111], off offset:576 nt
	v_lshlrev_b64 v[142:143], 12, v[114:115]
	v_lshl_add_u64 v[126:127], v[138:139], 0, v[142:143]
	global_load_dwordx4 v[114:117], v[126:127], off nt
	global_load_dwordx4 v[118:121], v[126:127], off offset:64 nt
	global_load_dwordx4 v[122:125], v[126:127], off offset:512 nt
	s_nop 0
	global_load_dwordx4 v[126:129], v[126:127], off offset:576 nt
	s_waitcnt vmcnt(7)
	v_pk_add_f32 v[94:95], v[94:95], v[98:99]
	v_lshl_add_u64 v[98:99], s[6:7], 0, v[148:149]
	v_lshl_add_u64 v[98:99], v[98:99], 0, v[136:137]
	s_waitcnt vmcnt(5)
	v_pk_add_f32 v[80:81], v[80:81], v[108:109]
	v_pk_add_f32 v[78:79], v[78:79], v[106:107]
	global_store_dwordx4 v[98:99], v[78:81], off offset:512
	s_waitcnt vmcnt(5)
	v_pk_add_f32 v[76:77], v[76:77], v[112:113]
	v_pk_add_f32 v[74:75], v[74:75], v[110:111]
	v_lshl_add_u64 v[78:79], s[6:7], 0, v[142:143]
	global_store_dwordx4 v[98:99], v[74:77], off offset:576
	v_lshl_add_u64 v[78:79], v[78:79], 0, v[136:137]
	v_pk_add_f32 v[96:97], v[96:97], v[100:101]
	s_waitcnt vmcnt(5)
	v_pk_add_f32 v[76:77], v[88:89], v[116:117]
	v_pk_add_f32 v[74:75], v[86:87], v[114:115]
	v_pk_add_f32 v[92:93], v[92:93], v[104:105]
	v_pk_add_f32 v[90:91], v[90:91], v[102:103]
	global_store_dwordx4 v[78:79], v[74:77], off
	s_waitcnt vmcnt(4)
	v_pk_add_f32 v[72:73], v[72:73], v[124:125]
	v_pk_add_f32 v[70:71], v[70:71], v[122:123]
	v_pk_add_f32 v[76:77], v[84:85], v[120:121]
	v_pk_add_f32 v[74:75], v[82:83], v[118:119]
	s_waitcnt vmcnt(3)
;     __device__ __forceinline__ void operator()(const f32x4 (&acc)[2][2][4][2], const Unit& u, int wr, int wc, int fr, int fq) const {
;     ...
;                 f32x4 xv[2][2][2];
; #pragma unroll
;                 for (int mm = 0; mm < 2; ++mm) { const size_t off = (size_t)(row0 + ai * HALF + (2 * m2 + mm) * 16) * 1024 + col0;
; #pragma unroll
;                     for (int bj = 0; bj < 2; ++bj)
; #pragma unroll
;                         for (int n = 0; n < 2; ++n) xv[mm][bj][n] = *(const f32x4*)(xin + off + bj * HALF + n * 16); }
; #pragma unroll
;                 for (int mm = 0; mm < 2; ++mm) { const size_t off = (size_t)(row0 + ai * HALF + (2 * m2 + mm) * 16) * 1024 + col0;
; #pragma unroll
;                     for (int bj = 0; bj < 2; ++bj)
; #pragma unroll
;                         for (int n = 0; n < 2; ++n) *(f32x4*)(out + off + bj * HALF + n * 16) = xv[mm][bj][n] + acc[ai][bj][2 * m2 + mm][n]; }
;                 asm volatile("" ::: "memory");
	v_pk_add_f32 v[68:69], v[68:69], v[128:129]
	v_pk_add_f32 v[66:67], v[66:67], v[126:127]
	global_store_dwordx4 v[98:99], v[94:97], off
	global_store_dwordx4 v[98:99], v[90:93], off offset:64
	global_store_dwordx4 v[78:79], v[74:77], off offset:64
	global_store_dwordx4 v[78:79], v[70:73], off offset:512
	global_store_dwordx4 v[78:79], v[66:69], off offset:576
	v_lshl_add_u64 v[98:99], v[140:141], 0, s[18:19]
	v_lshl_add_u64 v[78:79], v[138:139], 0, v[98:99]
	s_mov_b64 s[18:19], 0x90000
	global_load_dwordx4 v[66:69], v[78:79], off nt
	global_load_dwordx4 v[70:73], v[78:79], off offset:64 nt
	global_load_dwordx4 v[74:77], v[78:79], off offset:512 nt
	s_nop 0
	global_load_dwordx4 v[78:81], v[78:79], off offset:576 nt
	v_lshl_add_u64 v[100:101], v[140:141], 0, s[18:19]
	v_lshl_add_u64 v[94:95], v[138:139], 0, v[100:101]
	global_load_dwordx4 v[82:85], v[94:95], off nt
	global_load_dwordx4 v[86:89], v[94:95], off offset:64 nt
	global_load_dwordx4 v[90:93], v[94:95], off offset:512 nt
	s_nop 0
	global_load_dwordx4 v[94:97], v[94:95], off offset:576 nt
	s_mov_b64 s[18:19], 0xa0000
	s_waitcnt vmcnt(7)
	v_pk_add_f32 v[60:61], v[60:61], v[66:67]
	v_lshl_add_u64 v[66:67], s[6:7], 0, v[98:99]
	v_lshl_add_u64 v[66:67], v[66:67], 0, v[136:137]
	s_waitcnt vmcnt(5)
	v_pk_add_f32 v[46:47], v[46:47], v[76:77]
	v_pk_add_f32 v[44:45], v[44:45], v[74:75]
	global_store_dwordx4 v[66:67], v[44:47], off offset:512
	s_waitcnt vmcnt(5)
	v_pk_add_f32 v[42:43], v[42:43], v[80:81]
	v_pk_add_f32 v[40:41], v[40:41], v[78:79]
	v_lshl_add_u64 v[44:45], s[6:7], 0, v[100:101]
	global_store_dwordx4 v[66:67], v[40:43], off offset:576
	v_lshl_add_u64 v[44:45], v[44:45], 0, v[136:137]
	v_pk_add_f32 v[62:63], v[62:63], v[68:69]
	s_waitcnt vmcnt(5)
	v_pk_add_f32 v[42:43], v[54:55], v[84:85]
	v_pk_add_f32 v[40:41], v[52:53], v[82:83]
	v_pk_add_f32 v[58:59], v[58:59], v[72:73]
	v_pk_add_f32 v[56:57], v[56:57], v[70:71]
	global_store_dwordx4 v[44:45], v[40:43], off
	s_waitcnt vmcnt(4)
	v_pk_add_f32 v[38:39], v[38:39], v[92:93]
	v_pk_add_f32 v[36:37], v[36:37], v[90:91]
	v_pk_add_f32 v[42:43], v[50:51], v[88:89]
	v_pk_add_f32 v[40:41], v[48:49], v[86:87]
	s_waitcnt vmcnt(3)
	v_pk_add_f32 v[34:35], v[34:35], v[96:97]
	v_pk_add_f32 v[32:33], v[32:33], v[94:95]
	global_store_dwordx4 v[66:67], v[60:63], off
	global_store_dwordx4 v[66:67], v[56:59], off offset:64
	global_store_dwordx4 v[44:45], v[40:43], off offset:64
	global_store_dwordx4 v[44:45], v[36:39], off offset:512
	global_store_dwordx4 v[44:45], v[32:35], off offset:576
	v_lshl_add_u64 v[66:67], v[140:141], 0, s[18:19]
	s_mov_b64 s[18:19], 0xb0000
	v_lshl_add_u64 v[44:45], v[138:139], 0, v[66:67]
	v_lshl_add_u64 v[68:69], v[140:141], 0, s[18:19]
	global_load_dwordx4 v[32:35], v[44:45], off nt
	global_load_dwordx4 v[36:39], v[44:45], off offset:64 nt
	global_load_dwordx4 v[40:43], v[44:45], off offset:512 nt
	s_nop 0
	global_load_dwordx4 v[44:47], v[44:45], off offset:576 nt
	v_lshl_add_u64 v[60:61], v[138:139], 0, v[68:69]
	global_load_dwordx4 v[48:51], v[60:61], off nt
	global_load_dwordx4 v[52:55], v[60:61], off offset:64 nt
	global_load_dwordx4 v[56:59], v[60:61], off offset:512 nt
	s_nop 0
	global_load_dwordx4 v[60:63], v[60:61], off offset:576 nt
	s_mov_b64 s[18:19], -1
	s_waitcnt vmcnt(7)
	v_pk_add_f32 v[28:29], v[28:29], v[32:33]
	v_lshl_add_u64 v[32:33], s[6:7], 0, v[66:67]
	v_lshl_add_u64 v[32:33], v[32:33], 0, v[136:137]
	s_waitcnt vmcnt(5)
	v_pk_add_f32 v[18:19], v[18:19], v[42:43]
	v_pk_add_f32 v[16:17], v[16:17], v[40:41]
	global_store_dwordx4 v[32:33], v[16:19], off offset:512
	s_waitcnt vmcnt(5)
	v_pk_add_f32 v[14:15], v[14:15], v[46:47]
	v_pk_add_f32 v[12:13], v[12:13], v[44:45]
	v_lshl_add_u64 v[16:17], s[6:7], 0, v[68:69]
	v_pk_add_f32 v[30:31], v[30:31], v[34:35]
	v_pk_add_f32 v[26:27], v[26:27], v[38:39]
	v_pk_add_f32 v[24:25], v[24:25], v[36:37]
	global_store_dwordx4 v[32:33], v[12:15], off offset:576
	v_lshl_add_u64 v[16:17], v[16:17], 0, v[136:137]
	s_waitcnt vmcnt(4)
	v_pk_add_f32 v[10:11], v[10:11], v[54:55]
	v_pk_add_f32 v[14:15], v[22:23], v[50:51]
	v_pk_add_f32 v[12:13], v[20:21], v[48:49]
	v_pk_add_f32 v[8:9], v[8:9], v[52:53]
	s_waitcnt vmcnt(3)
	v_pk_add_f32 v[6:7], v[6:7], v[58:59]
	v_pk_add_f32 v[4:5], v[4:5], v[56:57]
	s_waitcnt vmcnt(2)
	v_pk_add_f32 v[2:3], v[2:3], v[62:63]
	v_pk_add_f32 v[0:1], v[0:1], v[60:61]
	global_store_dwordx4 v[32:33], v[28:31], off
	global_store_dwordx4 v[32:33], v[24:27], off offset:64
	global_store_dwordx4 v[16:17], v[12:15], off
	global_store_dwordx4 v[16:17], v[8:11], off offset:64
	global_store_dwordx4 v[16:17], v[4:7], off offset:512
	global_store_dwordx4 v[16:17], v[0:3], off offset:576
	s_cbranch_vccnz .LBB0_995
	s_andn2_b64 vcc, exec, s[0:1]
	s_cbranch_vccnz .LBB0_994
	s_barrier
	s_branch .LBB0_994

;     __device__ __forceinline__ void operator()(const f32x4 (&acc)[2][2][4][2], const Unit& u, int wr, int wc, int fr, int fq) const {
;         const int row0 = u.pm * BM + wr * 64 + fr, col0 = u.pn * BM + wc * 32 + 4 * fq;
; #pragma unroll
;         for (int ai = 0; ai < 2; ++ai)
; #pragma unroll
;             for (int m2 = 0; m2 < 2; ++m2) {
;                 f32x4 xv[2][2][2];
; #pragma unroll
;                 for (int mm = 0; mm < 2; ++mm) { const size_t off = (size_t)(row0 + ai * HALF + (2 * m2 + mm) * 16) * 1024 + col0;
; #pragma unroll
;                     for (int bj = 0; bj < 2; ++bj)
; #pragma unroll
;                         for (int n = 0; n < 2; ++n) xv[mm][bj][n] = *(const f32x4*)(xin + off + bj * HALF + n * 16); }
; #pragma unroll
;                 for (int mm = 0; mm < 2; ++mm) { const size_t off = (size_t)(row0 + ai * HALF + (2 * m2 + mm) * 16) * 1024 + col0;
; #pragma unroll
;                     for (int bj = 0; bj < 2; ++bj)
; #pragma unroll
;                         for (int n = 0; n < 2; ++n) *(f32x4*)(out + off + bj * HALF + n * 16) = xv[mm][bj][n] + acc[ai][bj][2 * m2 + mm][n]; }
;                 asm volatile("" ::: "memory");
.LBB0_1206:
	v_lshl_or_b32 v136, s51, 8, v146
	v_lshl_add_u32 v142, s52, 8, v144
	v_ashrrev_i32_e32 v137, 31, v136
	v_lshlrev_b64 v[136:137], 2, v[136:137]
	v_ashrrev_i32_e32 v143, 31, v142
	v_or_b32_e32 v164, 16, v142
	v_lshl_add_u64 v[138:139], s[8:9], 0, v[136:137]
	v_lshlrev_b64 v[140:141], 12, v[142:143]
	v_ashrrev_i32_e32 v165, 31, v164
	v_lshl_add_u64 v[160:161], v[138:139], 0, v[140:141]
	v_lshlrev_b64 v[180:181], 12, v[164:165]
	global_load_dwordx4 v[148:151], v[160:161], off nt
	global_load_dwordx4 v[152:155], v[160:161], off offset:64 nt
	global_load_dwordx4 v[156:159], v[160:161], off offset:512 nt
	s_nop 0
	global_load_dwordx4 v[160:163], v[160:161], off offset:576 nt
	v_lshl_add_u64 v[176:177], v[138:139], 0, v[180:181]
	global_load_dwordx4 v[164:167], v[176:177], off nt
	global_load_dwordx4 v[168:171], v[176:177], off offset:64 nt
	global_load_dwordx4 v[172:175], v[176:177], off offset:512 nt
	s_nop 0
	global_load_dwordx4 v[176:179], v[176:177], off offset:576 nt
	s_mov_b64 s[14:15], 0x80000
	s_and_b64 vcc, exec, s[4:5]
	s_waitcnt vmcnt(0)
	v_pk_add_f32 v[126:127], v[126:127], v[148:149]
	v_lshl_add_u64 v[148:149], s[8:9], 0, v[140:141]
	v_lshl_add_u64 v[148:149], v[148:149], 0, v[136:137]
	v_pk_add_f32 v[112:113], v[112:113], v[158:159]
	v_pk_add_f32 v[110:111], v[110:111], v[156:157]
	global_store_dwordx4 v[148:149], v[110:113], off offset:512
	v_pk_add_f32 v[108:109], v[108:109], v[162:163]
	v_pk_add_f32 v[106:107], v[106:107], v[160:161]
	v_lshl_add_u64 v[110:111], s[8:9], 0, v[180:181]
	v_lshl_add_u64 v[110:111], v[110:111], 0, v[136:137]
	v_pk_add_f32 v[100:101], v[100:101], v[178:179]
	v_pk_add_f32 v[98:99], v[98:99], v[176:177]
	global_store_dwordx4 v[148:149], v[106:109], off offset:576
	global_store_dwordx4 v[110:111], v[98:101], off offset:576
	v_pk_add_f32 v[128:129], v[128:129], v[150:151]
	v_pk_add_f32 v[108:109], v[120:121], v[166:167]
	v_pk_add_f32 v[106:107], v[118:119], v[164:165]
	v_or_b32_e32 v98, 32, v142
	v_pk_add_f32 v[124:125], v[124:125], v[154:155]
	v_pk_add_f32 v[122:123], v[122:123], v[152:153]
	global_store_dwordx4 v[110:111], v[106:109], off
	v_pk_add_f32 v[104:105], v[104:105], v[174:175]
	v_pk_add_f32 v[102:103], v[102:103], v[172:173]
	v_pk_add_f32 v[108:109], v[116:117], v[170:171]
	v_pk_add_f32 v[106:107], v[114:115], v[168:169]
	v_ashrrev_i32_e32 v99, 31, v98
	global_store_dwordx4 v[148:149], v[126:129], off
	global_store_dwordx4 v[148:149], v[122:125], off offset:64
	global_store_dwordx4 v[110:111], v[106:109], off offset:64
	global_store_dwordx4 v[110:111], v[102:105], off offset:512
	v_lshlrev_b64 v[148:149], 12, v[98:99]
	v_or_b32_e32 v114, 48, v142
	v_lshl_add_u64 v[110:111], v[138:139], 0, v[148:149]
	v_ashrrev_i32_e32 v115, 31, v114
	global_load_dwordx4 v[98:101], v[110:111], off nt
	global_load_dwordx4 v[102:105], v[110:111], off offset:64 nt
	global_load_dwordx4 v[106:109], v[110:111], off offset:512 nt
	s_nop 0
	global_load_dwordx4 v[110:113], v[110:111], off offset:576 nt
	v_lshlrev_b64 v[142:143], 12, v[114:115]
	v_lshl_add_u64 v[126:127], v[138:139], 0, v[142:143]
	global_load_dwordx4 v[114:117], v[126:127], off nt
	global_load_dwordx4 v[118:121], v[126:127], off offset:64 nt
	global_load_dwordx4 v[122:125], v[126:127], off offset:512 nt
	s_nop 0
	global_load_dwordx4 v[126:129], v[126:127], off offset:576 nt
	s_waitcnt vmcnt(7)
	v_pk_add_f32 v[94:95], v[94:95], v[98:99]
	v_lshl_add_u64 v[98:99], s[8:9], 0, v[148:149]
	v_lshl_add_u64 v[98:99], v[98:99], 0, v[136:137]
	s_waitcnt vmcnt(5)
	v_pk_add_f32 v[80:81], v[80:81], v[108:109]
	v_pk_add_f32 v[78:79], v[78:79], v[106:107]
	global_store_dwordx4 v[98:99], v[78:81], off offset:512
	s_waitcnt vmcnt(5)
	v_pk_add_f32 v[76:77], v[76:77], v[112:113]
	v_pk_add_f32 v[74:75], v[74:75], v[110:111]
	v_lshl_add_u64 v[78:79], s[8:9], 0, v[142:143]
	global_store_dwordx4 v[98:99], v[74:77], off offset:576
	v_lshl_add_u64 v[78:79], v[78:79], 0, v[136:137]
	v_pk_add_f32 v[96:97], v[96:97], v[100:101]
	s_waitcnt vmcnt(5)
	v_pk_add_f32 v[76:77], v[88:89], v[116:117]
	v_pk_add_f32 v[74:75], v[86:87], v[114:115]
	v_pk_add_f32 v[92:93], v[92:93], v[104:105]
	v_pk_add_f32 v[90:91], v[90:91], v[102:103]
	global_store_dwordx4 v[78:79], v[74:77], off
	s_waitcnt vmcnt(4)
	v_pk_add_f32 v[72:73], v[72:73], v[124:125]
	v_pk_add_f32 v[70:71], v[70:71], v[122:123]
	v_pk_add_f32 v[76:77], v[84:85], v[120:121]
	v_pk_add_f32 v[74:75], v[82:83], v[118:119]
	s_waitcnt vmcnt(3)
;     __device__ __forceinline__ void operator()(const f32x4 (&acc)[2][2][4][2], const Unit& u, int wr, int wc, int fr, int fq) const {
;     ...
;                 f32x4 xv[2][2][2];
; #pragma unroll
;                 for (int mm = 0; mm < 2; ++mm) { const size_t off = (size_t)(row0 + ai * HALF + (2 * m2 + mm) * 16) * 1024 + col0;
; #pragma unroll
;                     for (int bj = 0; bj < 2; ++bj)
; #pragma unroll
;                         for (int n = 0; n < 2; ++n) xv[mm][bj][n] = *(const f32x4*)(xin + off + bj * HALF + n * 16); }
; #pragma unroll
;                 for (int mm = 0; mm < 2; ++mm) { const size_t off = (size_t)(row0 + ai * HALF + (2 * m2 + mm) * 16) * 1024 + col0;
; #pragma unroll
;                     for (int bj = 0; bj < 2; ++bj)
; #pragma unroll
;                         for (int n = 0; n < 2; ++n) *(f32x4*)(out + off + bj * HALF + n * 16) = xv[mm][bj][n] + acc[ai][bj][2 * m2 + mm][n]; }
;                 asm volatile("" ::: "memory");
	v_pk_add_f32 v[68:69], v[68:69], v[128:129]
	v_pk_add_f32 v[66:67], v[66:67], v[126:127]
	global_store_dwordx4 v[98:99], v[94:97], off
	global_store_dwordx4 v[98:99], v[90:93], off offset:64
	global_store_dwordx4 v[78:79], v[74:77], off offset:64
	global_store_dwordx4 v[78:79], v[70:73], off offset:512
	global_store_dwordx4 v[78:79], v[66:69], off offset:576
	v_lshl_add_u64 v[98:99], v[140:141], 0, s[14:15]
	v_lshl_add_u64 v[78:79], v[138:139], 0, v[98:99]
	s_mov_b64 s[14:15], 0x90000
	global_load_dwordx4 v[66:69], v[78:79], off nt
	global_load_dwordx4 v[70:73], v[78:79], off offset:64 nt
	global_load_dwordx4 v[74:77], v[78:79], off offset:512 nt
	s_nop 0
	global_load_dwordx4 v[78:81], v[78:79], off offset:576 nt
	v_lshl_add_u64 v[100:101], v[140:141], 0, s[14:15]
	v_lshl_add_u64 v[94:95], v[138:139], 0, v[100:101]
	global_load_dwordx4 v[82:85], v[94:95], off nt
	global_load_dwordx4 v[86:89], v[94:95], off offset:64 nt
	global_load_dwordx4 v[90:93], v[94:95], off offset:512 nt
	s_nop 0
	global_load_dwordx4 v[94:97], v[94:95], off offset:576 nt
	s_mov_b64 s[14:15], 0xa0000
	s_waitcnt vmcnt(7)
	v_pk_add_f32 v[60:61], v[60:61], v[66:67]
	v_lshl_add_u64 v[66:67], s[8:9], 0, v[98:99]
	v_lshl_add_u64 v[66:67], v[66:67], 0, v[136:137]
	s_waitcnt vmcnt(5)
	v_pk_add_f32 v[46:47], v[46:47], v[76:77]
	v_pk_add_f32 v[44:45], v[44:45], v[74:75]
	global_store_dwordx4 v[66:67], v[44:47], off offset:512
	s_waitcnt vmcnt(5)
	v_pk_add_f32 v[42:43], v[42:43], v[80:81]
	v_pk_add_f32 v[40:41], v[40:41], v[78:79]
	v_lshl_add_u64 v[44:45], s[8:9], 0, v[100:101]
	global_store_dwordx4 v[66:67], v[40:43], off offset:576
	v_lshl_add_u64 v[44:45], v[44:45], 0, v[136:137]
	v_pk_add_f32 v[62:63], v[62:63], v[68:69]
	s_waitcnt vmcnt(5)
	v_pk_add_f32 v[42:43], v[54:55], v[84:85]
	v_pk_add_f32 v[40:41], v[52:53], v[82:83]
	v_pk_add_f32 v[58:59], v[58:59], v[72:73]
	v_pk_add_f32 v[56:57], v[56:57], v[70:71]
	global_store_dwordx4 v[44:45], v[40:43], off
	s_waitcnt vmcnt(4)
	v_pk_add_f32 v[38:39], v[38:39], v[92:93]
	v_pk_add_f32 v[36:37], v[36:37], v[90:91]
	v_pk_add_f32 v[42:43], v[50:51], v[88:89]
	v_pk_add_f32 v[40:41], v[48:49], v[86:87]
	s_waitcnt vmcnt(3)
	v_pk_add_f32 v[34:35], v[34:35], v[96:97]
	v_pk_add_f32 v[32:33], v[32:33], v[94:95]
	global_store_dwordx4 v[66:67], v[60:63], off
	global_store_dwordx4 v[66:67], v[56:59], off offset:64
	global_store_dwordx4 v[44:45], v[40:43], off offset:64
	global_store_dwordx4 v[44:45], v[36:39], off offset:512
	global_store_dwordx4 v[44:45], v[32:35], off offset:576
	v_lshl_add_u64 v[66:67], v[140:141], 0, s[14:15]
	s_mov_b64 s[14:15], 0xb0000
	v_lshl_add_u64 v[44:45], v[138:139], 0, v[66:67]
	v_lshl_add_u64 v[68:69], v[140:141], 0, s[14:15]
	global_load_dwordx4 v[32:35], v[44:45], off nt
	global_load_dwordx4 v[36:39], v[44:45], off offset:64 nt
	global_load_dwordx4 v[40:43], v[44:45], off offset:512 nt
	s_nop 0
	global_load_dwordx4 v[44:47], v[44:45], off offset:576 nt
	v_lshl_add_u64 v[60:61], v[138:139], 0, v[68:69]
	global_load_dwordx4 v[48:51], v[60:61], off nt
	global_load_dwordx4 v[52:55], v[60:61], off offset:64 nt
	global_load_dwordx4 v[56:59], v[60:61], off offset:512 nt
	s_nop 0
	global_load_dwordx4 v[60:63], v[60:61], off offset:576 nt
	s_mov_b64 s[14:15], -1
	s_waitcnt vmcnt(7)
	v_pk_add_f32 v[28:29], v[28:29], v[32:33]
	v_lshl_add_u64 v[32:33], s[8:9], 0, v[66:67]
	v_lshl_add_u64 v[32:33], v[32:33], 0, v[136:137]
	s_waitcnt vmcnt(5)
	v_pk_add_f32 v[18:19], v[18:19], v[42:43]
	v_pk_add_f32 v[16:17], v[16:17], v[40:41]
	global_store_dwordx4 v[32:33], v[16:19], off offset:512
	s_waitcnt vmcnt(5)
	v_pk_add_f32 v[14:15], v[14:15], v[46:47]
	v_pk_add_f32 v[12:13], v[12:13], v[44:45]
	v_lshl_add_u64 v[16:17], s[8:9], 0, v[68:69]
	v_pk_add_f32 v[30:31], v[30:31], v[34:35]
	v_pk_add_f32 v[26:27], v[26:27], v[38:39]
	v_pk_add_f32 v[24:25], v[24:25], v[36:37]
	global_store_dwordx4 v[32:33], v[12:15], off offset:576
	v_lshl_add_u64 v[16:17], v[16:17], 0, v[136:137]
	s_waitcnt vmcnt(4)
	v_pk_add_f32 v[10:11], v[10:11], v[54:55]
	v_pk_add_f32 v[14:15], v[22:23], v[50:51]
	v_pk_add_f32 v[12:13], v[20:21], v[48:49]
	v_pk_add_f32 v[8:9], v[8:9], v[52:53]
	s_waitcnt vmcnt(3)
	v_pk_add_f32 v[6:7], v[6:7], v[58:59]
	v_pk_add_f32 v[4:5], v[4:5], v[56:57]
	s_waitcnt vmcnt(2)
	v_pk_add_f32 v[2:3], v[2:3], v[62:63]
	v_pk_add_f32 v[0:1], v[0:1], v[60:61]
	global_store_dwordx4 v[32:33], v[28:31], off
	global_store_dwordx4 v[32:33], v[24:27], off offset:64
	global_store_dwordx4 v[16:17], v[12:15], off
	global_store_dwordx4 v[16:17], v[8:11], off offset:64
	global_store_dwordx4 v[16:17], v[4:7], off offset:512
	global_store_dwordx4 v[16:17], v[0:3], off offset:576
	s_cbranch_vccnz .LBB0_1191
	s_andn2_b64 vcc, exec, s[0:1]
	s_cbranch_vccnz .LBB0_1190
	s_barrier
	s_branch .LBB0_1190
